# retention: chunk-top vmcnt(0) no longer waits on previous chunk output stores (wait moved before stores)
# speedup vs baseline: 1.0063x; 1.0063x over previous
; #define LAS __attribute__((address_space(3)))
; __device__ __forceinline__ void ret_mfma(const Params& P, LAS unsigned char* lds, int wave) {
;     ...
;         const int xcd_ = unit & 7, idx_ = unit >> 3, bh = xcd_ * 4 + (idx_ >> 3), slice = idx_ & 7, b = bh >> 2, hh = bh & 3;
;         const float gam = 1.f - exp2f(-5.f - (float)hh), lg = log2f(gam), g64 = exp2f(lg * 64.f);
;         for (int i = t; i < 33792 / 16; i += NTHREADS) *(LAS u32x4*)(lds + ST_OFF + i * 16) = (u32x4){0u, 0u, 0u, 0u};
;         f32x16 st[2];
; #pragma unroll
;         for (int a = 0; a < 2; ++a)
; #pragma unroll
;             for (int i = 0; i < 16; ++i) st[a][i] = 0.f;
;         const size_t rb = (size_t)b * SEQ;
;         float dec[16];
;         { const int mblk = (wave & 3) >> 1, nblk = wave & 1, n = nblk * 32 + q32;
; #pragma unroll
;           for (int i = 0; i < 16; ++i) { const int mm = mblk * 32 + 8 * (i >> 2) + 4 * hf + (i & 3); const int dist = n > mm ? n - mm : mm - n;
;               dec[i] = wave < 4 ? __builtin_amdgcn_exp2f(lg * (float)(dist - (63 - mm))) : __builtin_amdgcn_exp2f(lg * (float)(n + 1)); } }
;         u32x4 pq[4], pkk[4], pvv;
;         const int vr = t >> 3, vc = t & 7;
; #pragma unroll
;         for (int i = 0; i < 4; ++i) { const int id = t + 512 * i, r = id >> 5, ch = id & 31;
;             pq[i] = *(const u32x4*)(QK + (rb + r) * 2048 + hh * 256 + ch * 8); pkk[i] = *(const u32x4*)(QK + (rb + r) * 2048 + 1024 + hh * 256 + ch * 8); }
;         pvv = *(const u32x4*)(V + (rb + vr) * 2048 + hh * 512 + slice * 64 + vc * 8);
.LBB0_252:
	s_or_b64 exec, exec, s[8:9]
	s_ashr_i32 s9, s28, 6
	s_and_b32 s23, s9, 3
	v_cvt_f32_ubyte0_e32 v0, s23
	v_sub_f32_e32 v0, 0xc0a00000, v0
	v_cmp_gt_f32_e32 vcc, s25, v0
	s_lshl_b32 s8, s28, 2
	s_and_b32 s8, s8, 28
	v_cndmask_b32_e32 v1, 0, v182, vcc
	v_add_f32_e32 v0, v0, v1
	s_add_i32 s8, s8, s9
	v_exp_f32_e32 v0, v0
	s_bfe_u32 s22, s28, 0x30003
	s_ashr_i32 s8, s8, 2
	s_and_b64 s[18:19], vcc, exec
	s_cselect_b32 s9, 0xffffffc0, 0
	v_ldexp_f32 v0, v0, s9
	v_sub_f32_e32 v0, 1.0, v0
	v_cmp_gt_f32_e32 vcc, s26, v0
	s_and_b64 s[18:19], vcc, exec
	s_cselect_b32 s9, 32, 0
	v_ldexp_f32 v0, v0, s9
	v_log_f32_e32 v2, v0
	v_cndmask_b32_e32 v1, 0, v183, vcc
	s_mov_b32 s21, s15
	v_mov_b32_e32 v103, v91
	v_sub_f32_e32 v1, v2, v1
	v_mul_f32_e32 v2, 0x42800000, v1
	v_cmp_gt_f32_e32 vcc, s25, v2
	s_and_b64 s[18:19], vcc, exec
	s_cselect_b32 s9, 0xffffffc0, 0
	v_cndmask_b32_e32 v2, 0, v182, vcc
	v_fmac_f32_e32 v2, 0x42800000, v1
	v_exp_f32_e32 v2, v2
	v_mul_f32_e32 v3, v1, v85
	v_mul_f32_e32 v4, v1, v152
	v_exp_f32_e32 v3, v3
	v_ldexp_f32 v106, v2, s9
	v_mul_f32_e32 v2, v1, v153
	v_exp_f32_e32 v105, v2
	v_mul_f32_e32 v2, v1, v154
	v_exp_f32_e32 v110, v2
	v_mul_f32_e32 v2, v1, v155
	v_exp_f32_e32 v111, v2
	v_mul_f32_e32 v2, v1, v156
	v_exp_f32_e32 v104, v4
	v_exp_f32_e32 v112, v2
	v_mul_f32_e32 v2, v1, v157
	v_exp_f32_e32 v113, v2
	v_mul_f32_e32 v2, v1, v158
	s_ashr_i32 s9, s8, 31
	v_exp_f32_e32 v114, v2
	v_mul_f32_e32 v2, v1, v159
	v_exp_f32_e32 v115, v2
	v_mul_f32_e32 v2, v1, v160
	s_lshl_b64 s[18:19], s[8:9], 12
	v_cndmask_b32_e64 v108, v3, v104, s[4:5]
	v_exp_f32_e32 v116, v2
	v_lshl_add_u64 v[2:3], s[18:19], 0, v[92:93]
	v_lshlrev_b64 v[2:3], 12, v[2:3]
	v_lshl_add_u64 v[2:3], s[44:45], 0, v[2:3]
	s_lshl_b32 s14, s23, 9
	v_lshl_add_u64 v[2:3], v[2:3], 0, s[14:15]
	v_lshl_add_u64 v[2:3], v[2:3], 0, v[90:91]
	s_waitcnt vmcnt(0)
	flat_load_dwordx4 v[48:51], v[2:3]
	flat_load_dwordx4 v[52:55], v[2:3] offset:2048
	v_lshl_add_u64 v[2:3], s[18:19], 0, v[94:95]
	v_lshlrev_b64 v[2:3], 12, v[2:3]
	v_lshl_add_u64 v[2:3], s[44:45], 0, v[2:3]
	v_lshl_add_u64 v[2:3], v[2:3], 0, s[14:15]
	v_lshl_add_u64 v[2:3], v[2:3], 0, v[90:91]
	flat_load_dwordx4 v[56:59], v[2:3]
	flat_load_dwordx4 v[60:63], v[2:3] offset:2048
	v_lshl_add_u64 v[2:3], s[18:19], 0, v[96:97]
	v_lshlrev_b64 v[2:3], 12, v[2:3]
	v_lshl_add_u64 v[2:3], s[44:45], 0, v[2:3]
	v_lshl_add_u64 v[2:3], v[2:3], 0, s[14:15]
	v_lshl_add_u64 v[2:3], v[2:3], 0, v[90:91]
	flat_load_dwordx4 v[64:67], v[2:3]
	flat_load_dwordx4 v[68:71], v[2:3] offset:2048
	v_lshl_add_u64 v[2:3], s[18:19], 0, v[98:99]
	v_lshlrev_b64 v[2:3], 12, v[2:3]
	v_lshl_add_u64 v[2:3], s[44:45], 0, v[2:3]
	v_lshl_add_u64 v[2:3], v[2:3], 0, s[14:15]
	v_lshl_add_u64 v[2:3], v[2:3], 0, v[90:91]
	flat_load_dwordx4 v[72:75], v[2:3]
	flat_load_dwordx4 v[76:79], v[2:3] offset:2048
	v_lshl_add_u64 v[2:3], s[18:19], 0, v[88:89]
	v_lshlrev_b64 v[2:3], 12, v[2:3]
	v_lshl_add_u64 v[2:3], s[36:37], 0, v[2:3]
	s_lshl_b32 s8, s23, 10
	s_mov_b32 s9, s15
	v_lshl_add_u64 v[2:3], v[2:3], 0, s[8:9]
	s_lshl_b32 s20, s22, 7
	v_lshl_add_u64 v[2:3], v[2:3], 0, s[20:21]
	v_lshl_add_u64 v[2:3], v[2:3], 0, v[102:103]
	flat_load_dwordx4 v[80:83], v[2:3]
	s_add_u32 s8, s36, s8
	s_addc_u32 s9, s37, 0
	s_add_u32 s8, s8, s20
	v_mul_f32_e32 v2, v1, v161
	s_addc_u32 s9, s9, 0
	s_lshl_b32 s20, s23, 6
	v_exp_f32_e32 v117, v2
	v_mul_f32_e32 v2, v1, v162
	s_add_u32 s20, s60, s20
	v_exp_f32_e32 v118, v2
	v_mul_f32_e32 v2, v1, v163
	s_addc_u32 s21, s61, 0
	s_lshl_b32 s22, s22, 3
	v_exp_f32_e32 v119, v2
	v_mul_f32_e32 v2, v1, v164
	s_add_u32 s20, s20, s22
	v_exp_f32_e32 v120, v2
	v_mul_f32_e32 v2, v1, v165
	s_addc_u32 s21, s21, 0
	v_exp_f32_e32 v121, v2
	v_mul_f32_e32 v2, v1, v166
	v_mul_f32_e32 v1, v1, v167
	s_add_u32 s20, s20, s16
	v_exp_f32_e32 v122, v2
	v_exp_f32_e32 v123, v1
	s_addc_u32 s21, s21, s17
	v_lshl_add_u64 v[124:125], s[8:9], 0, v[102:103]
	s_add_u32 s8, s8, s27
	v_mov_b32_e32 v0, 0
	s_addc_u32 s9, s9, 0
	s_mov_b32 s29, 0
	v_mov_b32_e32 v126, v106
	v_mov_b32_e32 v127, v106
	v_lshl_add_u64 v[128:129], v[86:87], 1, s[8:9]
	v_mov_b32_e32 v109, v108
	v_mov_b32_e32 v130, v108
	v_mov_b32_e32 v131, v108
	v_mov_b32_e32 v132, v108
	v_mov_b32_e32 v133, v108
	v_mov_b32_e32 v134, v108
	v_mov_b32_e32 v135, v108
	v_mov_b32_e32 v136, v108
	v_mov_b32_e32 v137, v108
	v_mov_b32_e32 v138, v108
	v_mov_b32_e32 v139, v108
	v_mov_b32_e32 v140, v108
	v_mov_b32_e32 v141, v108
	v_mov_b32_e32 v142, v108
	v_mov_b32_e32 v143, v108
	v_lshl_add_u64 v[144:145], v[100:101], 0, s[14:15]
	v_mov_b32_e32 v1, v0
	v_mov_b32_e32 v2, v0
	v_mov_b32_e32 v3, v0
	v_mov_b32_e32 v4, v0
	v_mov_b32_e32 v5, v0
	v_mov_b32_e32 v6, v0
	v_mov_b32_e32 v7, v0
	v_mov_b32_e32 v8, v0
	v_mov_b32_e32 v9, v0
	v_mov_b32_e32 v10, v0
	v_mov_b32_e32 v11, v0
	v_mov_b32_e32 v12, v0
	v_mov_b32_e32 v13, v0
	v_mov_b32_e32 v14, v0
	v_mov_b32_e32 v15, v0
	v_mov_b32_e32 v16, v0
	v_mov_b32_e32 v17, v0
	v_mov_b32_e32 v18, v0
	v_mov_b32_e32 v19, v0
	v_mov_b32_e32 v20, v0
	v_mov_b32_e32 v21, v0
	v_mov_b32_e32 v22, v0
	v_mov_b32_e32 v23, v0
	v_mov_b32_e32 v24, v0
	v_mov_b32_e32 v25, v0
	v_mov_b32_e32 v26, v0
	v_mov_b32_e32 v27, v0
	v_mov_b32_e32 v28, v0
	v_mov_b32_e32 v29, v0
	v_mov_b32_e32 v30, v0
	v_mov_b32_e32 v31, v0
	s_waitcnt vmcnt(0)
	s_branch .LBB0_255

; #define LAS __attribute__((address_space(3)))
; __device__ __forceinline__ void ret_mfma(const Params& P, LAS unsigned char* lds, int wave) {
;     ...
;         for (int c = 0; c < 64; ++c) {
; #pragma unroll
;             for (int i = 0; i < 4; ++i) { const int id = t + 512 * i, r = id >> 5, ch = id & 31;
;                 *(LAS u32x4*)(lds + Q_OFF + r * QP + ch * 16) = pq[i]; *(LAS u32x4*)(lds + K_OFF + r * QP + ch * 16) = pkk[i]; }
;             *(LAS u32x4*)(lds + V_OFF + vr * VP + vc * 16) = pvv;
;             __syncthreads();
;             if (c + 1 < 64) { const size_t r1 = rb + (size_t)(c + 1) * 64;
; #pragma unroll
;                 for (int i = 0; i < 4; ++i) { const int id = t + 512 * i, r = id >> 5, ch = id & 31;
;                     pq[i] = *(const u32x4*)(QK + (r1 + r) * 2048 + hh * 256 + ch * 8); pkk[i] = *(const u32x4*)(QK + (r1 + r) * 2048 + 1024 + hh * 256 + ch * 8); }
;                 pvv = *(const u32x4*)(V + (r1 + vr) * 2048 + hh * 512 + slice * 64 + vc * 8); }
.LBB0_255:
	s_add_i32 s14, s29, 1
	s_cmp_lg_u32 s29, 63
	s_waitcnt lgkmcnt(0)
	ds_write_b128 v173, v[48:51]
	ds_write_b128 v173, v[52:55] offset:33792
	ds_write_b128 v174, v[56:59]
	ds_write_b128 v174, v[60:63] offset:33792
	ds_write_b128 v175, v[64:67]
	ds_write_b128 v175, v[68:71] offset:33792
	ds_write_b128 v176, v[72:75]
	ds_write_b128 v176, v[76:79] offset:33792
	ds_write_b128 v177, v[80:83]
	s_waitcnt lgkmcnt(0)
	s_barrier
	s_cbranch_scc0 .LBB0_257
	s_lshl_b32 s8, s14, 6
	s_add_u32 s8, s18, s8
	s_addc_u32 s9, s19, 0
	v_lshl_add_u64 v[32:33], s[8:9], 0, v[92:93]
	v_lshlrev_b64 v[32:33], 12, v[32:33]
	v_lshl_add_u64 v[32:33], v[144:145], 0, v[32:33]
	flat_load_dwordx4 v[48:51], v[32:33]
	flat_load_dwordx4 v[52:55], v[32:33] offset:2048
	v_lshl_add_u64 v[32:33], s[8:9], 0, v[94:95]
	v_lshlrev_b64 v[32:33], 12, v[32:33]
	v_lshl_add_u64 v[32:33], v[144:145], 0, v[32:33]
	flat_load_dwordx4 v[56:59], v[32:33]
	flat_load_dwordx4 v[60:63], v[32:33] offset:2048
	v_lshl_add_u64 v[32:33], s[8:9], 0, v[96:97]
	v_lshlrev_b64 v[32:33], 12, v[32:33]
	v_lshl_add_u64 v[32:33], v[144:145], 0, v[32:33]
	flat_load_dwordx4 v[64:67], v[32:33]
	flat_load_dwordx4 v[68:71], v[32:33] offset:2048
	v_lshl_add_u64 v[32:33], s[8:9], 0, v[98:99]
	v_lshlrev_b64 v[32:33], 12, v[32:33]
	v_lshl_add_u64 v[32:33], v[144:145], 0, v[32:33]
	flat_load_dwordx4 v[72:75], v[32:33]
	flat_load_dwordx4 v[76:79], v[32:33] offset:2048
	v_lshl_add_u64 v[32:33], s[8:9], 0, v[88:89]
	v_lshlrev_b64 v[32:33], 12, v[32:33]
	v_lshl_add_u64 v[32:33], v[124:125], 0, v[32:33]
	flat_load_dwordx4 v[80:83], v[32:33]

; #define LAS __attribute__((address_space(3)))
; __device__ __forceinline__ unsigned cvt_pk_bf16(float lo, float hi) { f32x2 v = {lo, hi}; bf16x2_t b = __builtin_convertvector(v, bf16x2_t); return __builtin_bit_cast(unsigned, b); }
; __device__ __forceinline__ void ret_mfma(const Params& P, LAS unsigned char* lds, int wave) {
;     ...
;             {
; #pragma unroll
;                 for (int a = 0; a < 2; ++a) st[a] = st[a] * g64;
; #pragma unroll
;                 for (int ks = 0; ks < 4; ++ks) {
;                     bf16x8 av[2], bk;
; #pragma unroll
;                     for (int vb = 0; vb < 2; ++vb) { const LAS unsigned char* p = lds + V_OFF + (16 * ks + trrow) * VP + vb * 64 + trcol; av[vb] = tr_pair(p, p + 4 * VP); }
;                     { const LAS unsigned char* p = lds + K_OFF + (16 * ks + trrow) * QP + wave * 64 + trcol; bk = tr_pair(p, p + 4 * QP); }
; #pragma unroll
;                     for (int vb = 0; vb < 2; ++vb) st[vb] = __builtin_amdgcn_mfma_f32_32x32x16_bf16(av[vb], bk, st[vb], 0, 0, 0);
;                 }
; #pragma unroll
;                 for (int vb = 0; vb < 2; ++vb)
; #pragma unroll
;                     for (int i = 0; i < 16; ++i) { const int dv = vb * 32 + 8 * (i >> 2) + 4 * hf + (i & 3);
;                         *(LAS bf16_t*)(lds + ST_OFF + dv * QP + (wave * 32 + q32) * 2) = (bf16_t)(cvt_pk_bf16(st[vb][i], 0.f) & 0xffffu); }
;             }
.LBB0_265:
	v_add_u32_e32 v103, v148, v168
	s_waitcnt lgkmcnt(0)
	s_barrier
	ds_read_b64_tr_b16 v[190:191], v103
	ds_read_b64_tr_b16 v[192:193], v103 offset:768
	v_mov_b32_e32 v107, v106
	v_pk_mul_f32 v[14:15], v[106:107], v[14:15]
	v_pk_mul_f32 v[12:13], v[106:107], v[12:13]
	v_pk_mul_f32 v[10:11], v[106:107], v[10:11]
	v_pk_mul_f32 v[8:9], v[106:107], v[8:9]
	v_pk_mul_f32 v[6:7], v[106:107], v[6:7]
	v_pk_mul_f32 v[4:5], v[106:107], v[4:5]
	v_pk_mul_f32 v[2:3], v[106:107], v[2:3]
	v_pk_mul_f32 v[0:1], v[126:127], v[0:1]
	ds_read_b64_tr_b16 v[194:195], v179 offset:33792
	ds_read_b64_tr_b16 v[196:197], v179 offset:35904
	ds_read_b64_tr_b16 v[200:201], v103 offset:832
	ds_read_b64_tr_b16 v[198:199], v103 offset:64
	ds_read_b64_tr_b16 v[202:203], v179 offset:42240
	ds_read_b64_tr_b16 v[204:205], v179 offset:44352
	s_waitcnt lgkmcnt(0)
	v_mfma_f32_32x32x16_bf16 v[0:15], v[190:193], v[194:197], v[0:15]
	v_mul_f32_e64 v30, v106, v30
	v_mul_f32_e64 v31, v107, v31
	v_mul_f32_e64 v28, v106, v28
	v_mul_f32_e64 v29, v107, v29
	v_mul_f32_e64 v26, v106, v26
	v_mul_f32_e64 v27, v107, v27
	v_pk_mul_f32 v[24:25], v[106:107], v[24:25]
	v_pk_mul_f32 v[22:23], v[106:107], v[22:23]
	v_pk_mul_f32 v[20:21], v[106:107], v[20:21]
	v_pk_mul_f32 v[18:19], v[106:107], v[18:19]
	v_pk_mul_f32 v[16:17], v[126:127], v[16:17]
	s_and_b64 vcc, exec, s[8:9]
	s_nop 0
	v_mfma_f32_32x32x16_bf16 v[16:31], v[198:201], v[194:197], v[16:31]
	ds_read_b64_tr_b16 v[190:191], v103 offset:3072
	ds_read_b64_tr_b16 v[192:193], v103 offset:3840
	ds_read_b64_tr_b16 v[196:197], v103 offset:3904
	ds_read_b64_tr_b16 v[194:195], v103 offset:3136
	s_waitcnt lgkmcnt(0)
	v_mfma_f32_32x32x16_bf16 v[0:15], v[190:193], v[202:205], v[0:15]
	v_mfma_f32_32x32x16_bf16 v[16:31], v[194:197], v[202:205], v[16:31]
	ds_read_b64_tr_b16 v[190:191], v103 offset:6144
	ds_read_b64_tr_b16 v[192:193], v103 offset:6912
	ds_read_b64_tr_b16 v[194:195], v179 offset:50688
	ds_read_b64_tr_b16 v[196:197], v179 offset:52800
	ds_read_b64_tr_b16 v[200:201], v103 offset:6976
	ds_read_b64_tr_b16 v[198:199], v103 offset:6208
	ds_read_b64_tr_b16 v[202:203], v179 offset:59136
	ds_read_b64_tr_b16 v[204:205], v179 offset:61248
	s_waitcnt lgkmcnt(0)
	v_mfma_f32_32x32x16_bf16 v[0:15], v[190:193], v[194:197], v[0:15]
	ds_read_b64_tr_b16 v[190:191], v103 offset:9216
	ds_read_b64_tr_b16 v[192:193], v103 offset:9984
	ds_read_b64_tr_b16 v[208:209], v103 offset:10048
	ds_read_b64_tr_b16 v[206:207], v103 offset:9280
	s_waitcnt lgkmcnt(0)
	v_mfma_f32_32x32x16_bf16 v[0:15], v[190:193], v[202:205], v[0:15]
	v_mfma_f32_32x32x16_bf16 v[16:31], v[198:201], v[194:197], v[16:31]
	s_nop 10
	v_cvt_pk_bf16_f32 v103, v0, s0
	ds_write_b16 v180, v103
	v_cvt_pk_bf16_f32 v103, v1, s0
	ds_write_b16 v180, v103 offset:528
	v_cvt_pk_bf16_f32 v103, v2, s0
	ds_write_b16 v180, v103 offset:1056
	v_cvt_pk_bf16_f32 v103, v3, s0
	ds_write_b16 v180, v103 offset:1584
	v_cvt_pk_bf16_f32 v103, v4, s0
	ds_write_b16 v180, v103 offset:4224
	v_cvt_pk_bf16_f32 v103, v5, s0
	ds_write_b16 v180, v103 offset:4752
	v_cvt_pk_bf16_f32 v103, v6, s0
	ds_write_b16 v180, v103 offset:5280
	v_cvt_pk_bf16_f32 v103, v7, s0
	v_mfma_f32_32x32x16_bf16 v[16:31], v[206:209], v[202:205], v[16:31]
	ds_write_b16 v180, v103 offset:5808
	v_cvt_pk_bf16_f32 v103, v8, s0
	ds_write_b16 v180, v103 offset:8448
	v_cvt_pk_bf16_f32 v103, v9, s0
	ds_write_b16 v180, v103 offset:8976
	v_cvt_pk_bf16_f32 v103, v10, s0
	ds_write_b16 v180, v103 offset:9504
	v_cvt_pk_bf16_f32 v103, v11, s0
	ds_write_b16 v180, v103 offset:10032
	v_cvt_pk_bf16_f32 v103, v12, s0
	ds_write_b16 v180, v103 offset:12672
	v_cvt_pk_bf16_f32 v103, v13, s0
	ds_write_b16 v180, v103 offset:13200
	v_cvt_pk_bf16_f32 v103, v14, s0
	ds_write_b16 v180, v103 offset:13728
	v_cvt_pk_bf16_f32 v103, v15, s0
	ds_write_b16 v180, v103 offset:14256
	v_cvt_pk_bf16_f32 v103, v16, s0
	ds_write_b16 v180, v103 offset:16896
	v_cvt_pk_bf16_f32 v103, v17, s0
	ds_write_b16 v180, v103 offset:17424
	v_cvt_pk_bf16_f32 v103, v18, s0
	ds_write_b16 v180, v103 offset:17952
	v_cvt_pk_bf16_f32 v103, v19, s0
	ds_write_b16 v180, v103 offset:18480
	v_cvt_pk_bf16_f32 v103, v20, s0
	ds_write_b16 v180, v103 offset:21120
	v_cvt_pk_bf16_f32 v103, v21, s0
	ds_write_b16 v180, v103 offset:21648
	v_cvt_pk_bf16_f32 v103, v22, s0
	ds_write_b16 v180, v103 offset:22176
	v_cvt_pk_bf16_f32 v103, v23, s0
	ds_write_b16 v180, v103 offset:22704
	v_cvt_pk_bf16_f32 v103, v24, s0
	ds_write_b16 v180, v103 offset:25344
	v_cvt_pk_bf16_f32 v103, v25, s0
	ds_write_b16 v180, v103 offset:25872
	v_cvt_pk_bf16_f32 v103, v26, s0
	ds_write_b16 v180, v103 offset:26400
	v_cvt_pk_bf16_f32 v103, v27, s0
	ds_write_b16 v180, v103 offset:26928
	v_cvt_pk_bf16_f32 v103, v28, s0
	ds_write_b16 v180, v103 offset:29568
	v_cvt_pk_bf16_f32 v103, v29, s0
	ds_write_b16 v180, v103 offset:30096
	v_cvt_pk_bf16_f32 v103, v30, s0
	ds_write_b16 v180, v103 offset:30624
	v_cvt_pk_bf16_f32 v103, v31, s0
	ds_write_b16 v180, v103 offset:31152
	s_waitcnt vmcnt(0)
	s_cbranch_vccnz .LBB0_254
; #define LAS __attribute__((address_space(3)))
; __device__ __forceinline__ unsigned cvt_pk_bf16(float lo, float hi) { f32x2 v = {lo, hi}; bf16x2_t b = __builtin_convertvector(v, bf16x2_t); return __builtin_bit_cast(unsigned, b); }
; __device__ __forceinline__ void ret_mfma(const Params& P, LAS unsigned char* lds, int wave) {
;     ...
;             if (wave >= 4) {
;                 const int w4 = wave - 4, dvblk = w4 >> 1, nblk = w4 & 1, n = nblk * 32 + q32;
; #pragma unroll
;                 for (int ks = 0; ks < 4; ++ks) {
;                     const LAS unsigned char* p = lds + V_OFF + (16 * ks + trrow) * VP + dvblk * 64 + trcol;
;                     const bf16x8 a = tr_pair(p, p + 4 * VP);
;                     const bf16x8 bs = *(const LAS bf16x8*)(lds + S_OFF + n * SP + (16 * ks + 8 * hf) * 2);
;                     acc = __builtin_amdgcn_mfma_f32_32x32x16_bf16(a, bs, acc, 0, 0, 0);
;                 }
;                 float sq = 0.f;
; #pragma unroll
;                 for (int i = 0; i < 16; ++i) sq += acc[i] * acc[i];
;                 sq += __shfl_xor(sq, 32);
;                 if (hf == 0) rssq[(r0 + n) * 64 + hh * 16 + slice * 2 + dvblk] = sq;
;                 bf16_t* op = V + (r0 + n) * 2048 + hh * 512 + slice * 64 + dvblk * 32 + 4 * hf;
; #pragma unroll
;                 for (int j = 0; j < 4; ++j) { u32x2 w; w.x = cvt_pk_bf16(acc[4 * j], acc[4 * j + 1]); w.y = cvt_pk_bf16(acc[4 * j + 2], acc[4 * j + 3]); *(u32x2*)(op + 8 * j) = w; }
	ds_read_b64_tr_b16 v[190:191], v181
	ds_read_b64_tr_b16 v[192:193], v181 offset:768
	v_add_u32_e32 v103, v151, v149
	ds_read_b128 v[194:197], v103
	ds_read_b64_tr_b16 v[198:199], v181 offset:3072
	ds_read_b64_tr_b16 v[200:201], v181 offset:3840
	ds_read_b128 v[202:205], v103 offset:32
	v_and_b32_e32 v107, 64, v184
	v_add_u32_e32 v107, 64, v107
	s_waitcnt lgkmcnt(0)
	v_mfma_f32_32x32x16_bf16 v[32:47], v[190:193], v[194:197], v[32:47]
	s_lshl_b32 s8, s29, 6
	s_or_b32 s8, s18, s8
	v_or_b32_e32 v146, s8, v84
	v_mfma_f32_32x32x16_bf16 v[32:47], v[198:201], v[202:205], v[32:47]
	ds_read_b64_tr_b16 v[190:191], v181 offset:6144
	ds_read_b64_tr_b16 v[192:193], v181 offset:6912
	ds_read_b128 v[194:197], v103 offset:64
	ds_read_b64_tr_b16 v[198:199], v181 offset:9216
	ds_read_b64_tr_b16 v[200:201], v181 offset:9984
	ds_read_b128 v[202:205], v103 offset:96
	v_xor_b32_e32 v103, 32, v184
	v_cmp_lt_i32_e32 vcc, v103, v107
	s_nop 1
	v_cndmask_b32_e32 v107, v184, v103, vcc
	v_lshlrev_b32_e32 v107, 2, v107
	s_waitcnt lgkmcnt(0)
	v_mfma_f32_32x32x16_bf16 v[32:47], v[190:193], v[194:197], v[32:47]
	v_mfma_f32_32x32x16_bf16 v[32:47], v[198:201], v[202:205], v[32:47]
	s_nop 11
	v_mul_f32_e32 v103, v33, v33
	v_fmac_f32_e32 v103, v32, v32
	v_fmac_f32_e32 v103, v34, v34
	v_fmac_f32_e32 v103, v35, v35
	v_fmac_f32_e32 v103, v36, v36
	v_fmac_f32_e32 v103, v37, v37
	v_fmac_f32_e32 v103, v38, v38
	v_fmac_f32_e32 v103, v39, v39
	v_fmac_f32_e32 v103, v40, v40
	v_fmac_f32_e32 v103, v41, v41
	v_fmac_f32_e32 v103, v42, v42
	v_fmac_f32_e32 v103, v43, v43
	v_fmac_f32_e32 v103, v44, v44
	v_fmac_f32_e32 v103, v45, v45
	v_fmac_f32_e32 v103, v46, v46
	v_fmac_f32_e32 v103, v47, v47
	ds_bpermute_b32 v107, v107, v103
	s_and_saveexec_b64 s[8:9], s[6:7]
	s_xor_b64 s[8:9], exec, s[8:9]
	v_mov_b32_e32 v147, s19
	s_andn2_saveexec_b64 s[8:9], s[8:9]
	s_cbranch_execz .LBB0_253
	v_mov_b32_e32 v147, s19
	v_lshlrev_b64 v[190:191], 8, v[146:147]
	s_waitcnt lgkmcnt(0)
	v_add_f32_e32 v103, v103, v107
	v_lshl_add_u64 v[190:191], s[20:21], 0, v[190:191]
	flat_store_dword v[190:191], v103
	s_branch .LBB0_253
